# phase-2 conv loop rewritten by hand: conv weights/bias hoisted out of the loop, 4 tap loads issued together, next iteration prefetched (2 register sets)
# speedup vs baseline: 1.0026x; 1.0026x over previous
; __device__ __forceinline__ float bflo(unsigned w) { return __uint_as_float(w << 16); }
; __device__ __forceinline__ float bfhi(unsigned w) { return __uint_as_float(w & 0xffff0000u); }
; __global__ void __launch_bounds__(512, 2) mega(Params p, int ph_lo, int ph_hi) {
;     ...
;         for (int idx = gt; idx < NTOK * 128; idx += NGT) {
;             const int t = idx >> 7, c8 = (idx & 127) * 8, pos = t & (SEQ - 1);
;             float a[8];
;             { const f32x4 b0 = *(const f32x4*)(p.conv_b + c8), b1 = *(const f32x4*)(p.conv_b + c8 + 4); a[0] = b0[0]; a[1] = b0[1]; a[2] = b0[2]; a[3] = b0[3]; a[4] = b1[0]; a[5] = b1[1]; a[6] = b1[2]; a[7] = b1[3]; }
; #pragma unroll
;             for (int j = 0; j < 4; ++j) {
;                 if (pos - 3 + j >= 0) {
;                     const u32x4 xw = *(const u32x4*)(BIG + (size_t)(t - 3 + j) * INC + c8);
;                     const f32x4 w0 = *(const f32x4*)(p.conv_w + j * 1024 + c8), w1 = *(const f32x4*)(p.conv_w + j * 1024 + c8 + 4);
;                     a[0] += w0[0] * bflo(xw.x); a[1] += w0[1] * bfhi(xw.x); a[2] += w0[2] * bflo(xw.y); a[3] += w0[3] * bfhi(xw.y);
;                     a[4] += w1[0] * bflo(xw.z); a[5] += w1[1] * bfhi(xw.z); a[6] += w1[2] * bflo(xw.w); a[7] += w1[3] * bfhi(xw.w);
;                 }
;             }
;             u32x4 o; o.x = pk2(a[0], a[1]); o.y = pk2(a[2], a[3]); o.z = pk2(a[4], a[5]); o.w = pk2(a[6], a[7]);
;             *(u32x4*)(XN + (size_t)t * 1024 + c8) = o;
;         }
.LBB0_83:
	s_and_b32 s0, s93, 0xffffffc0
	v_mbcnt_lo_u32_b32 v20, -1, 0
	v_mbcnt_hi_u32_b32 v20, -1, v20
	s_nop 0
	v_add_u32_e32 v8, s0, v20
	v_lshl_add_u32 v9, s2, 9, v8
	s_mov_b32 s0, 0x200000
	v_cmp_gt_i32_e32 vcc, s0, v9
	s_and_saveexec_b64 s[0:1], vcc
	s_cbranch_execz .LBB0_92
	v_lshlrev_b32_e32 v21, 3, v9
	v_and_b32_e32 v12, 0x3f8, v21
	v_lshlrev_b32_e32 v10, 2, v12
	v_mov_b32_e32 v11, 0
	s_mov_b64 s[4:5], 0
	s_movk_i32 s18, 0x3000
	s_mov_b64 s[98:99], 0x3000
	s_mov_b32 s19, 0x1fffff
	global_load_dwordx4 v[96:99], v10, s[70:71]
	global_load_dwordx4 v[100:103], v10, s[70:71] offset:16
	global_load_dwordx4 v[104:107], v10, s[68:69]
	global_load_dwordx4 v[108:111], v10, s[68:69] offset:16
	v_add_u32_e32 v13, 0x1000, v10
	v_add_u32_e32 v22, 0x2000, v10
	v_add_u32_e32 v23, 0x3000, v10
	global_load_dwordx4 v[112:115], v13, s[68:69]
	global_load_dwordx4 v[116:119], v13, s[68:69] offset:16
	global_load_dwordx4 v[120:123], v22, s[68:69]
	global_load_dwordx4 v[124:127], v22, s[68:69] offset:16
	global_load_dwordx4 v[128:131], v23, s[68:69]
	global_load_dwordx4 v[132:135], v23, s[68:69] offset:16
	v_lshlrev_b32_e32 v12, 1, v12
	v_mov_b32_e32 v13, v11
	v_lshl_add_u64 v[168:169], s[72:73], 0, v[12:13]
	v_lshl_add_u64 v[170:171], s[76:77], 0, v[12:13]
	v_ashrrev_i32_e32 v14, 7, v9
	v_add_u32_e32 v27, -3, v14
	v_mad_i64_i32 v[28:29], s[12:13], v27, s18, v[168:169]
	v_lshl_add_u64 v[30:31], v[28:29], 0, s[98:99]
	v_lshl_add_u64 v[32:33], v[30:31], 0, s[98:99]
	v_lshl_add_u64 v[34:35], v[32:33], 0, s[98:99]
	global_load_dwordx4 v[136:139], v[28:29], off
	global_load_dwordx4 v[140:143], v[30:31], off
	global_load_dwordx4 v[144:147], v[32:33], off
	global_load_dwordx4 v[148:151], v[34:35], off
.Lcv_A:
	v_add_u32_e32 v25, s38, v9
	v_ashrrev_i32_e32 v26, 7, v25
	v_add_u32_e32 v27, -3, v26
	v_mad_i64_i32 v[28:29], s[12:13], v27, s18, v[168:169]
	v_lshl_add_u64 v[30:31], v[28:29], 0, s[98:99]
	v_lshl_add_u64 v[32:33], v[30:31], 0, s[98:99]
	v_lshl_add_u64 v[34:35], v[32:33], 0, s[98:99]
	global_load_dwordx4 v[152:155], v[28:29], off
	global_load_dwordx4 v[156:159], v[30:31], off
	global_load_dwordx4 v[160:163], v[32:33], off
	global_load_dwordx4 v[164:167], v[34:35], off
	v_and_b32_e32 v15, 0x1fff, v14
	v_cmp_lt_u32_e64 s[6:7], 2, v15
	v_cmp_lt_u32_e64 s[8:9], 1, v15
	v_cmp_ne_u32_e64 s[10:11], 0, v15
	v_ashrrev_i32_e32 v15, 31, v14
	v_lshlrev_b64 v[16:17], 11, v[14:15]
	v_lshl_add_u64 v[16:17], v[170:171], 0, v[16:17]
	s_waitcnt vmcnt(4)
	v_mov_b64_e32 v[4:5], v[96:97]
	v_mov_b64_e32 v[6:7], v[98:99]
	v_mov_b64_e32 v[0:1], v[100:101]
	v_mov_b64_e32 v[2:3], v[102:103]
	v_cndmask_b32_e64 v36, 0, v136, s[6:7]
	v_cndmask_b32_e64 v37, 0, v137, s[6:7]
	v_cndmask_b32_e64 v38, 0, v138, s[6:7]
	v_cndmask_b32_e64 v39, 0, v139, s[6:7]
	v_lshlrev_b32_e32 v40, 16, v36
	v_and_b32_e32 v41, 0xffff0000, v36
	v_lshlrev_b32_e32 v42, 16, v37
	v_and_b32_e32 v43, 0xffff0000, v37
	v_lshlrev_b32_e32 v44, 16, v38
	v_and_b32_e32 v45, 0xffff0000, v38
	v_lshlrev_b32_e32 v46, 16, v39
	v_and_b32_e32 v47, 0xffff0000, v39
	v_pk_fma_f32 v[4:5], v[104:105], v[40:41], v[4:5]
	v_pk_fma_f32 v[6:7], v[106:107], v[42:43], v[6:7]
	v_pk_fma_f32 v[0:1], v[108:109], v[44:45], v[0:1]
	v_pk_fma_f32 v[2:3], v[110:111], v[46:47], v[2:3]
	v_cndmask_b32_e64 v36, 0, v140, s[8:9]
	v_cndmask_b32_e64 v37, 0, v141, s[8:9]
	v_cndmask_b32_e64 v38, 0, v142, s[8:9]
	v_cndmask_b32_e64 v39, 0, v143, s[8:9]
	v_lshlrev_b32_e32 v40, 16, v36
	v_and_b32_e32 v41, 0xffff0000, v36
	v_lshlrev_b32_e32 v42, 16, v37
	v_and_b32_e32 v43, 0xffff0000, v37
	v_lshlrev_b32_e32 v44, 16, v38
	v_and_b32_e32 v45, 0xffff0000, v38
	v_lshlrev_b32_e32 v46, 16, v39
	v_and_b32_e32 v47, 0xffff0000, v39
	v_pk_fma_f32 v[4:5], v[112:113], v[40:41], v[4:5]
	v_pk_fma_f32 v[6:7], v[114:115], v[42:43], v[6:7]
	v_pk_fma_f32 v[0:1], v[116:117], v[44:45], v[0:1]
	v_pk_fma_f32 v[2:3], v[118:119], v[46:47], v[2:3]
	v_cndmask_b32_e64 v36, 0, v144, s[10:11]
	v_cndmask_b32_e64 v37, 0, v145, s[10:11]
	v_cndmask_b32_e64 v38, 0, v146, s[10:11]
	v_cndmask_b32_e64 v39, 0, v147, s[10:11]
	v_lshlrev_b32_e32 v40, 16, v36
	v_and_b32_e32 v41, 0xffff0000, v36
	v_lshlrev_b32_e32 v42, 16, v37
	v_and_b32_e32 v43, 0xffff0000, v37
	v_lshlrev_b32_e32 v44, 16, v38
	v_and_b32_e32 v45, 0xffff0000, v38
	v_lshlrev_b32_e32 v46, 16, v39
	v_and_b32_e32 v47, 0xffff0000, v39
	v_pk_fma_f32 v[4:5], v[120:121], v[40:41], v[4:5]
	v_pk_fma_f32 v[6:7], v[122:123], v[42:43], v[6:7]
	v_pk_fma_f32 v[0:1], v[124:125], v[44:45], v[0:1]
	v_pk_fma_f32 v[2:3], v[126:127], v[46:47], v[2:3]
	v_lshlrev_b32_e32 v40, 16, v148
	v_and_b32_e32 v41, 0xffff0000, v148
	v_lshlrev_b32_e32 v42, 16, v149
	v_and_b32_e32 v43, 0xffff0000, v149
	v_lshlrev_b32_e32 v44, 16, v150
	v_and_b32_e32 v45, 0xffff0000, v150
	v_lshlrev_b32_e32 v46, 16, v151
	v_and_b32_e32 v47, 0xffff0000, v151
	v_pk_fma_f32 v[4:5], v[128:129], v[40:41], v[4:5]
	v_pk_fma_f32 v[6:7], v[130:131], v[42:43], v[6:7]
	v_pk_fma_f32 v[0:1], v[132:133], v[44:45], v[0:1]
	v_pk_fma_f32 v[2:3], v[134:135], v[46:47], v[2:3]
	v_cvt_pk_bf16_f32 v36, v4, v5
	v_cvt_pk_bf16_f32 v37, v6, v7
	v_cvt_pk_bf16_f32 v38, v0, v1
	v_cvt_pk_bf16_f32 v39, v2, v3
	global_store_dwordx4 v[16:17], v[36:39], off
	v_mov_b32_e32 v9, v25
	v_mov_b32_e32 v14, v26
	v_cmp_lt_i32_e32 vcc, s19, v9
	s_or_b64 s[4:5], vcc, s[4:5]
	s_andn2_b64 exec, exec, s[4:5]
	s_cbranch_execz .LBB0_92
; __device__ __forceinline__ float bflo(unsigned w) { return __uint_as_float(w << 16); }
; __device__ __forceinline__ float bfhi(unsigned w) { return __uint_as_float(w & 0xffff0000u); }
; __global__ void __launch_bounds__(512, 2) mega(Params p, int ph_lo, int ph_hi) {
;     ...
;         for (int idx = gt; idx < NTOK * 128; idx += NGT) {
;             const int t = idx >> 7, c8 = (idx & 127) * 8, pos = t & (SEQ - 1);
;             float a[8];
;             { const f32x4 b0 = *(const f32x4*)(p.conv_b + c8), b1 = *(const f32x4*)(p.conv_b + c8 + 4); a[0] = b0[0]; a[1] = b0[1]; a[2] = b0[2]; a[3] = b0[3]; a[4] = b1[0]; a[5] = b1[1]; a[6] = b1[2]; a[7] = b1[3]; }
; #pragma unroll
;             for (int j = 0; j < 4; ++j) {
;                 if (pos - 3 + j >= 0) {
;                     const u32x4 xw = *(const u32x4*)(BIG + (size_t)(t - 3 + j) * INC + c8);
;                     const f32x4 w0 = *(const f32x4*)(p.conv_w + j * 1024 + c8), w1 = *(const f32x4*)(p.conv_w + j * 1024 + c8 + 4);
;                     a[0] += w0[0] * bflo(xw.x); a[1] += w0[1] * bfhi(xw.x); a[2] += w0[2] * bflo(xw.y); a[3] += w0[3] * bfhi(xw.y);
;                     a[4] += w1[0] * bflo(xw.z); a[5] += w1[1] * bfhi(xw.z); a[6] += w1[2] * bflo(xw.w); a[7] += w1[3] * bfhi(xw.w);
;                 }
;             }
;             u32x4 o; o.x = pk2(a[0], a[1]); o.y = pk2(a[2], a[3]); o.z = pk2(a[4], a[5]); o.w = pk2(a[6], a[7]);
;             *(u32x4*)(XN + (size_t)t * 1024 + c8) = o;
;         }
.Lcv_B:
	v_add_u32_e32 v25, s38, v9
	v_ashrrev_i32_e32 v26, 7, v25
	v_add_u32_e32 v27, -3, v26
	v_mad_i64_i32 v[28:29], s[12:13], v27, s18, v[168:169]
	v_lshl_add_u64 v[30:31], v[28:29], 0, s[98:99]
	v_lshl_add_u64 v[32:33], v[30:31], 0, s[98:99]
	v_lshl_add_u64 v[34:35], v[32:33], 0, s[98:99]
	global_load_dwordx4 v[136:139], v[28:29], off
	global_load_dwordx4 v[140:143], v[30:31], off
	global_load_dwordx4 v[144:147], v[32:33], off
	global_load_dwordx4 v[148:151], v[34:35], off
	v_and_b32_e32 v15, 0x1fff, v14
	v_cmp_lt_u32_e64 s[6:7], 2, v15
	v_cmp_lt_u32_e64 s[8:9], 1, v15
	v_cmp_ne_u32_e64 s[10:11], 0, v15
	v_ashrrev_i32_e32 v15, 31, v14
	v_lshlrev_b64 v[16:17], 11, v[14:15]
	v_lshl_add_u64 v[16:17], v[170:171], 0, v[16:17]
	s_waitcnt vmcnt(4)
	v_mov_b64_e32 v[4:5], v[96:97]
	v_mov_b64_e32 v[6:7], v[98:99]
	v_mov_b64_e32 v[0:1], v[100:101]
	v_mov_b64_e32 v[2:3], v[102:103]
	v_cndmask_b32_e64 v36, 0, v152, s[6:7]
	v_cndmask_b32_e64 v37, 0, v153, s[6:7]
	v_cndmask_b32_e64 v38, 0, v154, s[6:7]
	v_cndmask_b32_e64 v39, 0, v155, s[6:7]
	v_lshlrev_b32_e32 v40, 16, v36
	v_and_b32_e32 v41, 0xffff0000, v36
	v_lshlrev_b32_e32 v42, 16, v37
	v_and_b32_e32 v43, 0xffff0000, v37
	v_lshlrev_b32_e32 v44, 16, v38
	v_and_b32_e32 v45, 0xffff0000, v38
	v_lshlrev_b32_e32 v46, 16, v39
	v_and_b32_e32 v47, 0xffff0000, v39
	v_pk_fma_f32 v[4:5], v[104:105], v[40:41], v[4:5]
	v_pk_fma_f32 v[6:7], v[106:107], v[42:43], v[6:7]
	v_pk_fma_f32 v[0:1], v[108:109], v[44:45], v[0:1]
	v_pk_fma_f32 v[2:3], v[110:111], v[46:47], v[2:3]
	v_cndmask_b32_e64 v36, 0, v156, s[8:9]
	v_cndmask_b32_e64 v37, 0, v157, s[8:9]
	v_cndmask_b32_e64 v38, 0, v158, s[8:9]
	v_cndmask_b32_e64 v39, 0, v159, s[8:9]
	v_lshlrev_b32_e32 v40, 16, v36
	v_and_b32_e32 v41, 0xffff0000, v36
	v_lshlrev_b32_e32 v42, 16, v37
	v_and_b32_e32 v43, 0xffff0000, v37
	v_lshlrev_b32_e32 v44, 16, v38
	v_and_b32_e32 v45, 0xffff0000, v38
	v_lshlrev_b32_e32 v46, 16, v39
	v_and_b32_e32 v47, 0xffff0000, v39
	v_pk_fma_f32 v[4:5], v[112:113], v[40:41], v[4:5]
	v_pk_fma_f32 v[6:7], v[114:115], v[42:43], v[6:7]
	v_pk_fma_f32 v[0:1], v[116:117], v[44:45], v[0:1]
	v_pk_fma_f32 v[2:3], v[118:119], v[46:47], v[2:3]
	v_cndmask_b32_e64 v36, 0, v160, s[10:11]
	v_cndmask_b32_e64 v37, 0, v161, s[10:11]
	v_cndmask_b32_e64 v38, 0, v162, s[10:11]
	v_cndmask_b32_e64 v39, 0, v163, s[10:11]
	v_lshlrev_b32_e32 v40, 16, v36
	v_and_b32_e32 v41, 0xffff0000, v36
	v_lshlrev_b32_e32 v42, 16, v37
	v_and_b32_e32 v43, 0xffff0000, v37
	v_lshlrev_b32_e32 v44, 16, v38
	v_and_b32_e32 v45, 0xffff0000, v38
	v_lshlrev_b32_e32 v46, 16, v39
	v_and_b32_e32 v47, 0xffff0000, v39
	v_pk_fma_f32 v[4:5], v[120:121], v[40:41], v[4:5]
	v_pk_fma_f32 v[6:7], v[122:123], v[42:43], v[6:7]
	v_pk_fma_f32 v[0:1], v[124:125], v[44:45], v[0:1]
	v_pk_fma_f32 v[2:3], v[126:127], v[46:47], v[2:3]
	v_lshlrev_b32_e32 v40, 16, v164
	v_and_b32_e32 v41, 0xffff0000, v164
	v_lshlrev_b32_e32 v42, 16, v165
	v_and_b32_e32 v43, 0xffff0000, v165
	v_lshlrev_b32_e32 v44, 16, v166
	v_and_b32_e32 v45, 0xffff0000, v166
	v_lshlrev_b32_e32 v46, 16, v167
	v_and_b32_e32 v47, 0xffff0000, v167
	v_pk_fma_f32 v[4:5], v[128:129], v[40:41], v[4:5]
	v_pk_fma_f32 v[6:7], v[130:131], v[42:43], v[6:7]
	v_pk_fma_f32 v[0:1], v[132:133], v[44:45], v[0:1]
	v_pk_fma_f32 v[2:3], v[134:135], v[46:47], v[2:3]
	v_cvt_pk_bf16_f32 v36, v4, v5
	v_cvt_pk_bf16_f32 v37, v6, v7
	v_cvt_pk_bf16_f32 v38, v0, v1
	v_cvt_pk_bf16_f32 v39, v2, v3
	global_store_dwordx4 v[16:17], v[36:39], off
	v_mov_b32_e32 v9, v25
	v_mov_b32_e32 v14, v26
	v_cmp_lt_i32_e32 vcc, s19, v9
	s_or_b64 s[4:5], vcc, s[4:5]
	s_andn2_b64 exec, exec, s[4:5]
	s_cbranch_execz .LBB0_92
	s_branch .Lcv_A

; __global__ void __launch_bounds__(512, 2) mega(Params p, int ph_lo, int ph_hi) {
;     ...
;                 const int pc0 = 32 * wave + fr_, pc1 = pc0 + 16;
;                 attn_tile_init(t0, BIG, b, h, n, 0, lane); attn_tile_init(t1, BIG, b, h, n, 0, lane);
;                 attn_q_load(t0, BIG, (size_t)b * SEQ + 256 * n + pc0, h, lane); attn_q_load(t1, BIG, (size_t)b * SEQ + 256 * n + pc1, h, lane);
;                 int g = 0;
;                 while (g < 12 && 256 * n - 128 + 32 * g + 31 < 0) ++g;
;                 const int kidx = tid >> 4, ch = tid & 15;
;                 u32x4 rk, rv;
;                 { int mk = 256 * n - 128 + 32 * g + kidx; mk = mk < 0 ? 0 : mk; const size_t row = (size_t)b * SEQ + mk;
;                   rk = *(const u32x4*)(BIG + row * INC + 2048 + h * 128 + 8 * ch); rv = *(const u32x4*)(BIG + row * INC + 4096 + h * 128 + 8 * ch); }
;                 __syncthreads();
.LBB0_780:
	s_lshl_b32 s4, s68, 5
	s_add_i32 s6, s39, s4
	s_add_i32 s7, s7, s2
	s_and_b64 s[4:5], s[28:29], exec
	s_cselect_b32 s6, s6, s7
	s_cmpk_gt_i32 s6, 0x3ff
	s_mov_b64 s[4:5], -1
	s_cbranch_scc1 .LBB0_779
	s_ashr_i32 s4, s6, 9
	s_and_b32 s11, s6, 31
	s_ashr_i32 s5, s4, 31
	s_lshl_b64 s[42:43], s[4:5], 13
	s_lshl_b32 s10, s11, 8
	s_or_b32 s40, s42, s10
	s_mov_b32 s41, s43
	s_lshl_b32 s5, s6, 2
	s_and_b32 s12, s5, 0x780
	v_lshl_add_u64 v[2:3], s[40:41], 0, v[162:163]
	v_mov_b64_e32 v[4:5], s[72:73]
	s_sub_i32 s5, 0x80, s10
	v_mad_u64_u32 v[6:7], s[8:9], v2, s49, v[4:5]
	s_lshl_b32 s26, s12, 1
	s_max_i32 s5, s5, 0
	v_mad_i32_i24 v7, v3, s49, v7
	s_cmp_eq_u32 s11, 0
	v_lshl_add_u64 v[2:3], v[6:7], 0, s[26:27]
	s_cselect_b32 s7, 4, 5
	s_cmp_lg_u32 s5, 0
	v_lshl_add_u64 v[2:3], v[2:3], 0, v[178:179]
	s_cselect_b32 s5, s7, 0
	global_load_dwordx4 v[8:11], v[2:3], off
	global_load_dwordx4 v[16:19], v[2:3], off offset:64
	global_load_dwordx4 v[20:23], v[2:3], off offset:128
	global_load_dwordx4 v[24:27], v[2:3], off offset:192
	v_lshl_add_u64 v[2:3], s[40:41], 0, v[164:165]
	s_lshl_b32 s15, s5, 5
	v_mad_u64_u32 v[6:7], s[8:9], v2, s49, v[4:5]
	s_or_b32 s7, s15, s10
	v_mad_i32_i24 v7, v3, s49, v7
	s_add_i32 s8, s7, 0xffffff80
	v_lshl_add_u64 v[2:3], v[6:7], 0, s[26:27]
	v_add_u32_e32 v0, s8, v196
	v_lshl_add_u64 v[2:3], v[2:3], 0, v[178:179]
	v_max_i32_e32 v0, 0, v0
	global_load_dwordx4 v[36:39], v[2:3], off
	global_load_dwordx4 v[44:47], v[2:3], off offset:64
	global_load_dwordx4 v[52:55], v[2:3], off offset:128
	global_load_dwordx4 v[56:59], v[2:3], off offset:192
	v_lshl_add_u64 v[2:3], s[42:43], 0, v[0:1]
	v_mad_u64_u32 v[4:5], s[8:9], v2, s49, v[4:5]
	v_mad_i32_i24 v5, v3, s49, v5
	v_mov_b32_e32 v181, v1
	v_lshl_add_u64 v[2:3], v[4:5], 0, s[26:27]
	v_lshl_add_u64 v[2:3], v[2:3], 0, v[180:181]
	v_add_co_u32_e32 v2, vcc, s51, v2
	v_add_u32_e32 v0, s7, v169
	s_nop 0
	v_addc_co_u32_e32 v3, vcc, 0, v3, vcc
	global_load_dwordx4 v[80:83], v[2:3], off offset:-4096
	global_load_dwordx4 v[92:95], v[2:3], off
	v_mad_i64_i32 v[2:3], s[8:9], v0, s49, 0
	s_add_i32 s14, s5, -1
	v_mad_i64_i32 v[2:3], s[4:5], s4, v213, v[2:3]
	s_lshl_b32 s4, s6, 3
	s_and_b32 s4, s4, 0xf00
	v_or_b32_e32 v2, s4, v2
	s_waitcnt vmcnt(0)
	v_lshl_add_u64 v[108:109], v[174:175], 0, v[2:3]
	v_mov_b32_e32 v2, v1
	v_mov_b32_e32 v3, v1
	v_mov_b32_e32 v0, v1
	v_mov_b64_e32 v[66:67], v[2:3]
	v_mov_b64_e32 v[70:71], v[2:3]
	v_mov_b64_e32 v[74:75], v[2:3]
	v_mov_b64_e32 v[78:79], v[2:3]
	v_mov_b64_e32 v[86:87], v[2:3]
	v_mov_b64_e32 v[90:91], v[2:3]
	v_mov_b64_e32 v[98:99], v[2:3]
	v_mov_b64_e32 v[106:107], v[2:3]
	v_mov_b64_e32 v[6:7], v[2:3]
	v_mov_b64_e32 v[14:15], v[2:3]
	v_mov_b64_e32 v[30:31], v[2:3]
	v_mov_b64_e32 v[34:35], v[2:3]
	v_mov_b64_e32 v[42:43], v[2:3]
	v_mov_b64_e32 v[50:51], v[2:3]
	v_mov_b64_e32 v[62:63], v[2:3]
	v_mov_b64_e32 v[102:103], v[2:3]
	s_mov_b32 s13, 0
	v_subrev_u32_e32 v117, s15, v207
	v_add_u32_e32 v118, s7, v208
	s_addk_i32 s15, 0xfea0
	v_mov_b32_e32 v119, 0
	v_mov_b32_e32 v112, 0xff800000
	s_mov_b32 s16, 0
	v_mov_b64_e32 v[64:65], v[0:1]
	v_mov_b64_e32 v[68:69], v[0:1]
	v_mov_b64_e32 v[72:73], v[0:1]
	v_mov_b64_e32 v[76:77], v[0:1]
	v_mov_b64_e32 v[84:85], v[0:1]
	v_mov_b64_e32 v[88:89], v[0:1]
	v_mov_b64_e32 v[96:97], v[0:1]
	v_mov_b64_e32 v[104:105], v[0:1]
	v_mov_b64_e32 v[4:5], v[0:1]
	v_mov_b64_e32 v[12:13], v[0:1]
	v_mov_b64_e32 v[28:29], v[0:1]
	v_mov_b64_e32 v[32:33], v[0:1]
	v_mov_b64_e32 v[40:41], v[0:1]
	v_mov_b64_e32 v[48:49], v[0:1]
	v_mov_b64_e32 v[60:61], v[0:1]
	v_mov_b64_e32 v[100:101], v[0:1]
	v_mov_b32_e32 v0, 0xff800000
	v_mov_b32_e32 v116, 0
	s_waitcnt vmcnt(0)
	s_barrier
	s_branch .LBB0_784

; #define LAS __attribute__((address_space(3)))
; __global__ void __launch_bounds__(512, 2) mega(Params p, int ph_lo, int ph_hi) {
;     ...
;                 for (; g < 12; ++g) {
;                     const int mk0 = 256 * n - 128 + 32 * g;
;                     LAS unsigned char* SK = lds + buf * 17408; LAS unsigned char* SV = SK + 8704;
;                     *(LAS u32x4*)(SK + (kidx * HP + 8 * ch) * 2) = rk; *(LAS u32x4*)(SV + (kidx * HP + 8 * ch) * 2) = rv;
;                     __syncthreads();
;                     if (g + 1 < 12) { const size_t row = (size_t)b * SEQ + (mk0 + 32 + kidx);
;                         rk = *(const u32x4*)(BIG + row * INC + 2048 + h * 128 + 8 * ch); rv = *(const u32x4*)(BIG + row * INC + 4096 + h * 128 + 8 * ch); }
.LBB0_784:
	s_mul_i32 s4, s16, 0x4400
	s_add_i32 s17, s4, 0
	v_add_u32_e32 v2, s17, v197
	s_cmp_eq_u32 s15, s13
	s_waitcnt vmcnt(1)
	ds_write_b128 v2, v[80:83]
	s_waitcnt vmcnt(0)
	ds_write_b128 v2, v[92:95] offset:8704
	s_waitcnt lgkmcnt(0)
	s_barrier
	s_cbranch_scc1 .LBB0_786
	v_add_co_u32_e32 v2, vcc, 0x1000, v108
	s_nop 1
	v_addc_co_u32_e32 v3, vcc, 0, v109, vcc
	global_load_dwordx4 v[80:83], v[108:109], off
	global_load_dwordx4 v[92:95], v[2:3], off
